# swiglu GEMM epilogue rewritten by hand: next-tile row scales prefetched at epilogue start and reduced at its end, silu batched with packed f32, 32-bit store offsets
# speedup vs baseline: 1.0068x; 1.0033x over previous
.LBB0_938:
	s_lshl_b32 s5, s8, 5
	s_and_b32 s8, s5, 0x60
	s_add_i32 m0, s47, 0x18000
	v_lshl_add_u64 v[6:7], v[6:7], 0, s[22:23]
	s_lshl_b32 s18, s2, 13
	s_lshl_b32 s19, s8, 7
	s_waitcnt vmcnt(2)
	s_barrier
	global_load_lds_dwordx4 v[6:7], off
	v_lshl_add_u64 v[4:5], v[4:5], 0, s[22:23]
	s_add_i32 m0, s47, 0x1a000
	s_add_i32 s73, s47, 0x8000
	s_add_i32 s74, s47, 0xa000
	global_load_lds_dwordx4 v[4:5], off
	v_lshl_add_u64 v[0:1], v[0:1], 0, s[22:23]
	s_mov_b32 m0, s73
	s_add_u32 s14, s66, 0x40080
	global_load_lds_dwordx4 v[0:1], off
	v_lshl_add_u64 v[0:1], v[2:3], 0, s[22:23]
	s_mov_b32 m0, s74
	s_addc_u32 s15, s67, 0
	global_load_lds_dwordx4 v[0:1], off
	s_add_i32 m0, s47, 0x1c000
	v_lshl_add_u64 v[0:1], s[14:15], 0, v[96:97]
	global_load_lds_dwordx4 v[0:1], off
	v_lshl_add_u64 v[0:1], s[14:15], 0, v[154:155]
	s_add_i32 m0, s47, 0x1e000
	v_bfe_u32 v2, v198, 4, 2
	global_load_lds_dwordx4 v[0:1], off
	v_and_b32_e32 v1, 15, v198
	v_lshlrev_b32_e32 v0, 4, v2
	v_lshlrev_b32_e32 v3, 2, v198
	v_lshl_or_b32 v185, s2, 6, v1
	v_lshl_or_b32 v1, v1, 6, v0
	v_and_b32_e32 v3, 32, v3
	v_bitop3_b32 v4, v1, s18, v3 bitop3:0xde
	v_bitop3_b32 v187, s19, v1, v3 bitop3:0xf6
	v_mov_b32_e32 v1, v97
	v_lshl_add_u64 v[160:161], s[56:57], 0, v[0:1]
	v_lshlrev_b32_e32 v0, 14, v8
	v_and_b32_e32 v0, 0xffff8000, v0
	v_lshl_add_u32 v0, v9, 11, v0
	v_and_b32_e32 v1, 1, v8
	v_lshl_or_b32 v0, v1, 6, v0
	v_lshl_add_u32 v162, v10, 1, v0
	v_lshlrev_b32_e32 v0, 14, v12
	v_and_b32_e32 v0, 0xffff8000, v0
	s_waitcnt vmcnt(6)
	v_lshl_add_u32 v0, v11, 11, v0
	v_and_b32_e32 v1, 1, v12
	s_cmpk_lt_u32 s1, 0x100
	v_lshl_or_b32 v0, v1, 6, v0
	s_sext_i32_i16 s5, s0
	s_cselect_b64 s[58:59], -1, 0
	s_ashr_i32 s75, s34, 31
	v_lshl_or_b32 v190, v2, 3, s8
	v_mov_b32_e32 v163, v97
	v_lshl_add_u32 v164, v13, 1, v0
	v_mov_b32_e32 v165, v97
	s_mov_b32 s76, 0
	v_add_u32_e32 v191, 0, v4
	s_mov_b32 s60, s4
	v_lshl_add_u32 v199, s4, 8, v185
	v_mov_b32_e32 v251, 0
	v_lshlrev_b32_e32 v250, 6, v199
	v_lshl_add_u64 v[194:195], v[160:161], 0, v[250:251]
	global_load_dwordx4 v[200:203], v[194:195], off
	v_add_u32_e32 v250, 0x10, v199
	v_lshlrev_b32_e32 v250, 6, v250
	v_lshl_add_u64 v[194:195], v[160:161], 0, v[250:251]
	global_load_dwordx4 v[204:207], v[194:195], off
	v_add_u32_e32 v250, 0x20, v199
	v_lshlrev_b32_e32 v250, 6, v250
	v_lshl_add_u64 v[194:195], v[160:161], 0, v[250:251]
	global_load_dwordx4 v[150:153], v[194:195], off
	v_add_u32_e32 v250, 0x30, v199
	v_lshlrev_b32_e32 v250, 6, v250
	v_lshl_add_u64 v[194:195], v[160:161], 0, v[250:251]
	global_load_dwordx4 v[146:149], v[194:195], off
	v_add_u32_e32 v250, 0x80, v199
	v_lshlrev_b32_e32 v250, 6, v250
	v_lshl_add_u64 v[194:195], v[160:161], 0, v[250:251]
	global_load_dwordx4 v[142:145], v[194:195], off
	v_add_u32_e32 v250, 0x90, v199
	v_lshlrev_b32_e32 v250, 6, v250
	v_lshl_add_u64 v[194:195], v[160:161], 0, v[250:251]
	global_load_dwordx4 v[138:141], v[194:195], off
	v_add_u32_e32 v250, 0xa0, v199
	v_lshlrev_b32_e32 v250, 6, v250
	v_lshl_add_u64 v[194:195], v[160:161], 0, v[250:251]
	global_load_dwordx4 v[134:137], v[194:195], off
	v_add_u32_e32 v250, 0xb0, v199
	v_lshlrev_b32_e32 v250, 6, v250
	v_lshl_add_u64 v[194:195], v[160:161], 0, v[250:251]
	global_load_dwordx4 v[130:133], v[194:195], off
	s_waitcnt vmcnt(0)
	v_xor_b32_e32 v250, 16, v248
	v_xor_b32_e32 v251, 32, v248
	v_lshlrev_b32_e32 v250, 2, v250
	v_lshlrev_b32_e32 v251, 2, v251
	v_mov_b32_e32 v199, 0x358637bd
	v_add_f32_e32 v200, v201, v200
	v_add_f32_e32 v202, v202, v203
	v_add_f32_e32 v204, v205, v204
	v_add_f32_e32 v206, v206, v207
	v_add_f32_e32 v150, v151, v150
	v_add_f32_e32 v152, v152, v153
	v_add_f32_e32 v146, v147, v146
	v_add_f32_e32 v148, v148, v149
	v_add_f32_e32 v142, v143, v142
	v_add_f32_e32 v144, v144, v145
	v_add_f32_e32 v138, v139, v138
	v_add_f32_e32 v140, v140, v141
	v_add_f32_e32 v134, v135, v134
	v_add_f32_e32 v136, v136, v137
	v_add_f32_e32 v130, v131, v130
	v_add_f32_e32 v132, v132, v133
	v_add_f32_e32 v200, v200, v202
	v_add_f32_e32 v204, v204, v206
	v_add_f32_e32 v150, v150, v152
	v_add_f32_e32 v146, v146, v148
	v_add_f32_e32 v142, v142, v144
	v_add_f32_e32 v138, v138, v140
	v_add_f32_e32 v134, v134, v136
	v_add_f32_e32 v130, v130, v132
	ds_bpermute_b32 v201, v250, v200
	ds_bpermute_b32 v205, v250, v204
	ds_bpermute_b32 v151, v250, v150
	ds_bpermute_b32 v147, v250, v146
	ds_bpermute_b32 v143, v250, v142
	ds_bpermute_b32 v139, v250, v138
	ds_bpermute_b32 v135, v250, v134
	ds_bpermute_b32 v131, v250, v130
	s_waitcnt lgkmcnt(0)
	v_add_f32_e32 v200, v200, v201
	v_add_f32_e32 v204, v204, v205
	v_add_f32_e32 v150, v150, v151
	v_add_f32_e32 v146, v146, v147
	v_add_f32_e32 v142, v142, v143
	v_add_f32_e32 v138, v138, v139
	v_add_f32_e32 v134, v134, v135
	v_add_f32_e32 v130, v130, v131
	ds_bpermute_b32 v201, v251, v200
	ds_bpermute_b32 v205, v251, v204
	ds_bpermute_b32 v151, v251, v150
	ds_bpermute_b32 v147, v251, v146
	ds_bpermute_b32 v143, v251, v142
	ds_bpermute_b32 v139, v251, v138
	ds_bpermute_b32 v135, v251, v134
	ds_bpermute_b32 v131, v251, v130
	s_waitcnt lgkmcnt(0)
	v_add_f32_e32 v200, v200, v201
	v_add_f32_e32 v204, v204, v205
	v_add_f32_e32 v150, v150, v151
	v_add_f32_e32 v146, v146, v147
	v_add_f32_e32 v142, v142, v143
	v_add_f32_e32 v138, v138, v139
	v_add_f32_e32 v134, v134, v135
	v_add_f32_e32 v130, v130, v131
	v_fma_f32 v200, v200, s28, v199
	v_fma_f32 v204, v204, s28, v199
	v_fma_f32 v150, v150, s28, v199
	v_fma_f32 v146, v146, s28, v199
	v_fma_f32 v142, v142, s28, v199
	v_fma_f32 v138, v138, s28, v199
	v_fma_f32 v134, v134, s28, v199
	v_fma_f32 v130, v130, s28, v199
	v_rsq_f32_e32 v228, v200
	v_rsq_f32_e32 v230, v204
	v_rsq_f32_e32 v232, v150
	v_rsq_f32_e32 v234, v146
	v_rsq_f32_e32 v236, v142
	v_rsq_f32_e32 v238, v138
	v_rsq_f32_e32 v242, v134
	v_rsq_f32_e32 v244, v130
	s_barrier
	s_branch .LBB0_941

.LBB0_944:
	s_add_u32 s2, s66, 0xfffc0080
	s_addc_u32 s14, s67, -1
	s_add_i32 s15, 0, 0x10000
	s_cmp_eq_u32 s42, 12
	s_cselect_b32 s27, s18, s14
	s_cselect_b32 s26, s19, s2
	s_cselect_b32 s25, s8, s68
	s_cselect_b32 s24, s57, s61
	s_add_i32 s2, 0, 0x14000
	v_add_u32_e32 v142, s15, v187
	v_add_u32_e32 v170, s2, v187
	ds_read_b128 v[130:133], v142
	ds_read_b128 v[134:137], v142 offset:1024
	ds_read_b128 v[138:141], v142 offset:2048
	ds_read_b128 v[142:145], v142 offset:3072
	ds_read_b128 v[146:149], v170
	ds_read_b128 v[150:153], v170 offset:1024
	ds_read_b128 v[166:169], v170 offset:2048
	ds_read_b128 v[170:173], v170 offset:3072
	v_lshl_add_u64 v[182:183], s[66:67], 0, v[164:165]
	s_add_i32 m0, s47, 0xc000
	ds_read_b128 v[174:177], v191
	ds_read_b128 v[178:181], v191 offset:1024
	ds_read_b128 v[200:203], v191 offset:2048
	ds_read_b128 v[204:207], v191 offset:3072
	ds_read_b128 v[208:211], v191 offset:4096
	ds_read_b128 v[212:215], v191 offset:5120
	ds_read_b128 v[216:219], v191 offset:6144
	ds_read_b128 v[220:223], v191 offset:7168
	global_load_lds_dwordx4 v[182:183], off
	v_lshl_add_u64 v[182:183], s[66:67], 0, v[162:163]
	s_add_i32 m0, s47, 0xe000
	s_nop 0
	global_load_lds_dwordx4 v[182:183], off
	s_waitcnt vmcnt(8)
	s_waitcnt lgkmcnt(0)
	s_barrier
	s_setprio 1
	s_waitcnt lgkmcnt(0)
	v_mfma_f32_16x16x32_bf16 v[126:129], v[130:133], v[174:177], v[126:129]
	v_mfma_f32_16x16x32_bf16 v[118:121], v[138:141], v[174:177], v[118:121]
	v_mfma_f32_16x16x32_bf16 v[110:113], v[130:133], v[200:203], v[110:113]
	v_mfma_f32_16x16x32_bf16 v[102:105], v[138:141], v[200:203], v[102:105]
	v_mfma_f32_16x16x32_bf16 v[92:95], v[130:133], v[208:211], v[92:95]
	v_mfma_f32_16x16x32_bf16 v[84:87], v[138:141], v[208:211], v[84:87]
	v_mfma_f32_16x16x32_bf16 v[76:79], v[130:133], v[216:219], v[76:79]
	v_mfma_f32_16x16x32_bf16 v[68:71], v[138:141], v[216:219], v[68:71]
	v_mfma_f32_16x16x32_bf16 v[126:129], v[134:137], v[178:181], v[126:129]
	v_mfma_f32_16x16x32_bf16 v[118:121], v[142:145], v[178:181], v[118:121]
	v_mfma_f32_16x16x32_bf16 v[110:113], v[134:137], v[204:207], v[110:113]
	v_mfma_f32_16x16x32_bf16 v[102:105], v[142:145], v[204:207], v[102:105]
	v_mfma_f32_16x16x32_bf16 v[92:95], v[134:137], v[212:215], v[92:95]
	v_mfma_f32_16x16x32_bf16 v[84:87], v[142:145], v[212:215], v[84:87]
	v_mfma_f32_16x16x32_bf16 v[76:79], v[134:137], v[220:223], v[76:79]
	v_mfma_f32_16x16x32_bf16 v[68:71], v[142:145], v[220:223], v[68:71]
	s_setprio 0
	s_setprio 1
	v_mfma_f32_16x16x32_bf16 v[122:125], v[146:149], v[174:177], v[122:125]
	v_mfma_f32_16x16x32_bf16 v[114:117], v[166:169], v[174:177], v[114:117]
	v_mfma_f32_16x16x32_bf16 v[106:109], v[146:149], v[200:203], v[106:109]
	v_mfma_f32_16x16x32_bf16 v[98:101], v[166:169], v[200:203], v[98:101]
	v_mfma_f32_16x16x32_bf16 v[88:91], v[146:149], v[208:211], v[88:91]
	v_mfma_f32_16x16x32_bf16 v[80:83], v[166:169], v[208:211], v[80:83]
	v_mfma_f32_16x16x32_bf16 v[72:75], v[146:149], v[216:219], v[72:75]
	v_mfma_f32_16x16x32_bf16 v[64:67], v[166:169], v[216:219], v[64:67]
	v_mfma_f32_16x16x32_bf16 v[122:125], v[150:153], v[178:181], v[122:125]
	v_mfma_f32_16x16x32_bf16 v[114:117], v[170:173], v[178:181], v[114:117]
	v_mfma_f32_16x16x32_bf16 v[106:109], v[150:153], v[204:207], v[106:109]
	v_mfma_f32_16x16x32_bf16 v[98:101], v[170:173], v[204:207], v[98:101]
	v_mfma_f32_16x16x32_bf16 v[88:91], v[150:153], v[212:215], v[88:91]
	v_mfma_f32_16x16x32_bf16 v[80:83], v[170:173], v[212:215], v[80:83]
	v_mfma_f32_16x16x32_bf16 v[72:75], v[150:153], v[220:223], v[72:75]
	v_mfma_f32_16x16x32_bf16 v[64:67], v[170:173], v[220:223], v[64:67]
	s_setprio 0
	s_barrier
	s_add_i32 s14, s15, s39
	v_lshl_add_u64 v[182:183], s[24:25], 0, v[96:97]
	s_mov_b32 m0, s14
	ds_read_b128 v[174:177], v191 offset:16384
	ds_read_b128 v[178:181], v191 offset:17408
	ds_read_b128 v[200:203], v191 offset:18432
	ds_read_b128 v[204:207], v191 offset:19456
	ds_read_b128 v[208:211], v191 offset:20480
	ds_read_b128 v[212:215], v191 offset:21504
	ds_read_b128 v[216:219], v191 offset:22528
	ds_read_b128 v[220:223], v191 offset:23552
	global_load_lds_dwordx4 v[182:183], off
	s_add_i32 m0, s14, 0x2000
	s_add_u32 s14, s24, 0x40000
	v_lshl_add_u64 v[188:189], s[24:25], 0, v[154:155]
	s_addc_u32 s15, s25, 0
	s_add_i32 s2, s2, s39
	global_load_lds_dwordx4 v[188:189], off
	v_lshl_add_u64 v[192:193], s[14:15], 0, v[96:97]
	s_mov_b32 m0, s2
	v_lshl_add_u64 v[224:225], s[26:27], 0, v[156:157]
	global_load_lds_dwordx4 v[192:193], off
	v_lshl_add_u64 v[192:193], s[14:15], 0, v[154:155]
	s_add_i32 m0, s2, 0x2000
	s_nop 0
	global_load_lds_dwordx4 v[192:193], off
	v_lshl_add_u64 v[192:193], s[26:27], 0, v[158:159]
	s_mov_b32 m0, s47
	s_nop 0
	global_load_lds_dwordx4 v[192:193], off
	s_mov_b32 m0, s70
	s_nop 0
	global_load_lds_dwordx4 v[224:225], off
	s_waitcnt vmcnt(8)
	s_waitcnt lgkmcnt(0)
	s_barrier
	s_setprio 1
	s_waitcnt lgkmcnt(0)
	v_mfma_f32_16x16x32_bf16 v[60:63], v[130:133], v[174:177], v[60:63]
	v_mfma_f32_16x16x32_bf16 v[52:55], v[138:141], v[174:177], v[52:55]
	v_mfma_f32_16x16x32_bf16 v[44:47], v[130:133], v[200:203], v[44:47]
	v_mfma_f32_16x16x32_bf16 v[36:39], v[138:141], v[200:203], v[36:39]
	v_mfma_f32_16x16x32_bf16 v[28:31], v[130:133], v[208:211], v[28:31]
	v_mfma_f32_16x16x32_bf16 v[20:23], v[138:141], v[208:211], v[20:23]
	v_mfma_f32_16x16x32_bf16 v[12:15], v[130:133], v[216:219], v[12:15]
	v_mfma_f32_16x16x32_bf16 v[4:7], v[138:141], v[216:219], v[4:7]
	v_mfma_f32_16x16x32_bf16 v[60:63], v[134:137], v[178:181], v[60:63]
	v_mfma_f32_16x16x32_bf16 v[52:55], v[142:145], v[178:181], v[52:55]
	v_mfma_f32_16x16x32_bf16 v[44:47], v[134:137], v[204:207], v[44:47]
	v_mfma_f32_16x16x32_bf16 v[36:39], v[142:145], v[204:207], v[36:39]
	v_mfma_f32_16x16x32_bf16 v[28:31], v[134:137], v[212:215], v[28:31]
	v_mfma_f32_16x16x32_bf16 v[20:23], v[142:145], v[212:215], v[20:23]
	v_mfma_f32_16x16x32_bf16 v[12:15], v[134:137], v[220:223], v[12:15]
	v_mfma_f32_16x16x32_bf16 v[4:7], v[142:145], v[220:223], v[4:7]
	s_setprio 0
	s_setprio 1
	v_mfma_f32_16x16x32_bf16 v[56:59], v[146:149], v[174:177], v[56:59]
	v_mfma_f32_16x16x32_bf16 v[48:51], v[166:169], v[174:177], v[48:51]
	v_mfma_f32_16x16x32_bf16 v[40:43], v[146:149], v[200:203], v[40:43]
	v_mfma_f32_16x16x32_bf16 v[32:35], v[166:169], v[200:203], v[32:35]
	v_mfma_f32_16x16x32_bf16 v[24:27], v[146:149], v[208:211], v[24:27]
	v_mfma_f32_16x16x32_bf16 v[16:19], v[166:169], v[208:211], v[16:19]
	v_mfma_f32_16x16x32_bf16 v[8:11], v[146:149], v[216:219], v[8:11]
	v_mfma_f32_16x16x32_bf16 v[0:3], v[166:169], v[216:219], v[0:3]
	v_mfma_f32_16x16x32_bf16 v[56:59], v[150:153], v[178:181], v[56:59]
	v_mfma_f32_16x16x32_bf16 v[48:51], v[170:173], v[178:181], v[48:51]
	v_mfma_f32_16x16x32_bf16 v[40:43], v[150:153], v[204:207], v[40:43]
	v_mfma_f32_16x16x32_bf16 v[32:35], v[170:173], v[204:207], v[32:35]
	v_mfma_f32_16x16x32_bf16 v[24:27], v[150:153], v[212:215], v[24:27]
	v_mfma_f32_16x16x32_bf16 v[16:19], v[170:173], v[212:215], v[16:19]
	v_mfma_f32_16x16x32_bf16 v[8:11], v[150:153], v[220:223], v[8:11]
	v_mfma_f32_16x16x32_bf16 v[0:3], v[170:173], v[220:223], v[0:3]
	s_setprio 0
	s_barrier
	s_add_i32 s2, 0, 0x18000
	s_add_i32 s20, 0, 0x1c000
	v_add_u32_e32 v142, s2, v187
	v_add_u32_e32 v170, s20, v187
	ds_read_b128 v[130:133], v142
	ds_read_b128 v[134:137], v142 offset:1024
	ds_read_b128 v[138:141], v142 offset:2048
	ds_read_b128 v[142:145], v142 offset:3072
	ds_read_b128 v[146:149], v170
	ds_read_b128 v[150:153], v170 offset:1024
	ds_read_b128 v[166:169], v170 offset:2048
	ds_read_b128 v[170:173], v170 offset:3072
	s_add_u32 s14, s26, 0x40000
	s_addc_u32 s15, s27, 0
	s_mov_b32 m0, s71
	v_lshl_add_u64 v[226:227], s[14:15], 0, v[158:159]
	ds_read_b128 v[174:177], v191 offset:32768
	ds_read_b128 v[178:181], v191 offset:33792
	ds_read_b128 v[200:203], v191 offset:34816
	ds_read_b128 v[204:207], v191 offset:35840
	ds_read_b128 v[208:211], v191 offset:36864
	ds_read_b128 v[212:215], v191 offset:37888
	ds_read_b128 v[216:219], v191 offset:38912
	ds_read_b128 v[220:223], v191 offset:39936
	global_load_lds_dwordx4 v[226:227], off
	v_lshl_add_u64 v[226:227], s[14:15], 0, v[156:157]
	s_mov_b32 m0, s72
	s_nop 0
	global_load_lds_dwordx4 v[226:227], off
	s_waitcnt vmcnt(8)
	s_waitcnt lgkmcnt(0)
	s_barrier
	s_setprio 1
	s_waitcnt lgkmcnt(0)
	v_mfma_f32_16x16x32_bf16 v[126:129], v[130:133], v[174:177], v[126:129]
	v_mfma_f32_16x16x32_bf16 v[118:121], v[138:141], v[174:177], v[118:121]
	v_mfma_f32_16x16x32_bf16 v[110:113], v[130:133], v[200:203], v[110:113]
	v_mfma_f32_16x16x32_bf16 v[102:105], v[138:141], v[200:203], v[102:105]
	v_mfma_f32_16x16x32_bf16 v[92:95], v[130:133], v[208:211], v[92:95]
	v_mfma_f32_16x16x32_bf16 v[84:87], v[138:141], v[208:211], v[84:87]
	v_mfma_f32_16x16x32_bf16 v[76:79], v[130:133], v[216:219], v[76:79]
	v_mfma_f32_16x16x32_bf16 v[68:71], v[138:141], v[216:219], v[68:71]
	v_mfma_f32_16x16x32_bf16 v[126:129], v[134:137], v[178:181], v[126:129]
	v_mfma_f32_16x16x32_bf16 v[118:121], v[142:145], v[178:181], v[118:121]
	v_mfma_f32_16x16x32_bf16 v[110:113], v[134:137], v[204:207], v[110:113]
	v_mfma_f32_16x16x32_bf16 v[102:105], v[142:145], v[204:207], v[102:105]
	v_mfma_f32_16x16x32_bf16 v[92:95], v[134:137], v[212:215], v[92:95]
	v_mfma_f32_16x16x32_bf16 v[84:87], v[142:145], v[212:215], v[84:87]
	v_mfma_f32_16x16x32_bf16 v[76:79], v[134:137], v[220:223], v[76:79]
	v_mfma_f32_16x16x32_bf16 v[68:71], v[142:145], v[220:223], v[68:71]
	s_setprio 0
	s_setprio 1
	v_mfma_f32_16x16x32_bf16 v[122:125], v[146:149], v[174:177], v[122:125]
	v_mfma_f32_16x16x32_bf16 v[114:117], v[166:169], v[174:177], v[114:117]
	v_mfma_f32_16x16x32_bf16 v[106:109], v[146:149], v[200:203], v[106:109]
	v_mfma_f32_16x16x32_bf16 v[98:101], v[166:169], v[200:203], v[98:101]
	v_mfma_f32_16x16x32_bf16 v[88:91], v[146:149], v[208:211], v[88:91]
	v_mfma_f32_16x16x32_bf16 v[80:83], v[166:169], v[208:211], v[80:83]
	v_mfma_f32_16x16x32_bf16 v[72:75], v[146:149], v[216:219], v[72:75]
	v_mfma_f32_16x16x32_bf16 v[64:67], v[166:169], v[216:219], v[64:67]
	v_mfma_f32_16x16x32_bf16 v[122:125], v[150:153], v[178:181], v[122:125]
	v_mfma_f32_16x16x32_bf16 v[114:117], v[170:173], v[178:181], v[114:117]
	v_mfma_f32_16x16x32_bf16 v[106:109], v[150:153], v[204:207], v[106:109]
	v_mfma_f32_16x16x32_bf16 v[98:101], v[170:173], v[204:207], v[98:101]
	v_mfma_f32_16x16x32_bf16 v[88:91], v[150:153], v[212:215], v[88:91]
	v_mfma_f32_16x16x32_bf16 v[80:83], v[170:173], v[212:215], v[80:83]
	v_mfma_f32_16x16x32_bf16 v[72:75], v[150:153], v[220:223], v[72:75]
	v_mfma_f32_16x16x32_bf16 v[64:67], v[170:173], v[220:223], v[64:67]
	s_setprio 0
	s_barrier
	s_add_i32 s2, s2, s39
	v_lshl_add_u64 v[182:183], v[182:183], 0, s[22:23]
	s_mov_b32 m0, s2
	ds_read_b128 v[174:177], v191 offset:49152
	ds_read_b128 v[178:181], v191 offset:50176
	ds_read_b128 v[200:203], v191 offset:51200
	ds_read_b128 v[204:207], v191 offset:52224
	ds_read_b128 v[208:211], v191 offset:53248
	ds_read_b128 v[212:215], v191 offset:54272
	ds_read_b128 v[216:219], v191 offset:55296
	ds_read_b128 v[220:223], v191 offset:56320
	global_load_lds_dwordx4 v[182:183], off
	s_add_i32 m0, s2, 0x2000
	s_add_u32 s14, s24, 0x40080
	v_lshl_add_u64 v[182:183], v[188:189], 0, s[22:23]
	s_addc_u32 s15, s25, 0
	s_add_i32 s2, s20, s39
	global_load_lds_dwordx4 v[182:183], off
	v_lshl_add_u64 v[182:183], s[14:15], 0, v[96:97]
	s_mov_b32 m0, s2
	s_nop 0
	global_load_lds_dwordx4 v[182:183], off
	v_lshl_add_u64 v[182:183], s[14:15], 0, v[154:155]
	s_add_i32 m0, s2, 0x2000
	s_nop 0
	global_load_lds_dwordx4 v[182:183], off
	v_lshl_add_u64 v[182:183], v[192:193], 0, s[22:23]
	s_mov_b32 m0, s73
	s_nop 0
	global_load_lds_dwordx4 v[182:183], off
	v_lshl_add_u64 v[182:183], v[224:225], 0, s[22:23]
	s_mov_b32 m0, s74
	s_nop 0
	global_load_lds_dwordx4 v[182:183], off
	s_waitcnt vmcnt(8)
	s_waitcnt lgkmcnt(0)
	s_barrier
	s_setprio 1
	s_waitcnt lgkmcnt(0)
	v_mfma_f32_16x16x32_bf16 v[60:63], v[130:133], v[174:177], v[60:63]
	v_mfma_f32_16x16x32_bf16 v[52:55], v[138:141], v[174:177], v[52:55]
	v_mfma_f32_16x16x32_bf16 v[44:47], v[130:133], v[200:203], v[44:47]
	v_mfma_f32_16x16x32_bf16 v[36:39], v[138:141], v[200:203], v[36:39]
	v_mfma_f32_16x16x32_bf16 v[28:31], v[130:133], v[208:211], v[28:31]
	v_mfma_f32_16x16x32_bf16 v[20:23], v[138:141], v[208:211], v[20:23]
	v_mfma_f32_16x16x32_bf16 v[12:15], v[130:133], v[216:219], v[12:15]
	v_mfma_f32_16x16x32_bf16 v[4:7], v[138:141], v[216:219], v[4:7]
	v_mfma_f32_16x16x32_bf16 v[60:63], v[134:137], v[178:181], v[60:63]
	v_mfma_f32_16x16x32_bf16 v[52:55], v[142:145], v[178:181], v[52:55]
	v_mfma_f32_16x16x32_bf16 v[44:47], v[134:137], v[204:207], v[44:47]
	v_mfma_f32_16x16x32_bf16 v[36:39], v[142:145], v[204:207], v[36:39]
	v_mfma_f32_16x16x32_bf16 v[28:31], v[134:137], v[212:215], v[28:31]
	v_mfma_f32_16x16x32_bf16 v[20:23], v[142:145], v[212:215], v[20:23]
	v_mfma_f32_16x16x32_bf16 v[12:15], v[134:137], v[220:223], v[12:15]
	v_mfma_f32_16x16x32_bf16 v[4:7], v[142:145], v[220:223], v[4:7]
	s_setprio 0
	s_setprio 1
	v_mfma_f32_16x16x32_bf16 v[56:59], v[146:149], v[174:177], v[56:59]
	v_mfma_f32_16x16x32_bf16 v[48:51], v[166:169], v[174:177], v[48:51]
	v_mfma_f32_16x16x32_bf16 v[40:43], v[146:149], v[200:203], v[40:43]
	v_mfma_f32_16x16x32_bf16 v[32:35], v[166:169], v[200:203], v[32:35]
	v_mfma_f32_16x16x32_bf16 v[24:27], v[146:149], v[208:211], v[24:27]
	v_mfma_f32_16x16x32_bf16 v[16:19], v[166:169], v[208:211], v[16:19]
	v_mfma_f32_16x16x32_bf16 v[8:11], v[146:149], v[216:219], v[8:11]
	v_mfma_f32_16x16x32_bf16 v[0:3], v[166:169], v[216:219], v[0:3]
	v_mfma_f32_16x16x32_bf16 v[56:59], v[150:153], v[178:181], v[56:59]
	v_mfma_f32_16x16x32_bf16 v[48:51], v[170:173], v[178:181], v[48:51]
	v_mfma_f32_16x16x32_bf16 v[40:43], v[150:153], v[204:207], v[40:43]
	v_mfma_f32_16x16x32_bf16 v[32:35], v[170:173], v[204:207], v[32:35]
	v_mfma_f32_16x16x32_bf16 v[24:27], v[150:153], v[212:215], v[24:27]
	v_mfma_f32_16x16x32_bf16 v[16:19], v[170:173], v[212:215], v[16:19]
	v_mfma_f32_16x16x32_bf16 v[8:11], v[150:153], v[220:223], v[8:11]
	v_mfma_f32_16x16x32_bf16 v[0:3], v[170:173], v[220:223], v[0:3]
	s_setprio 0
	s_barrier
	s_add_i32 s42, s42, 2
	s_add_u32 s61, s61, 0x100
	s_addc_u32 s68, s68, 0
	s_add_u32 s66, s66, 0x100
	s_addc_u32 s67, s67, 0
	s_cmp_gt_u32 s42, 13
	s_cbranch_scc0 .LBB0_944
	v_lshl_add_u32 v180, s4, 8, v185
	v_lshl_add_u32 v199, s60, 8, v185
	v_mov_b32_e32 v251, 0
	v_lshlrev_b32_e32 v250, 6, v199
	v_lshl_add_u64 v[194:195], v[160:161], 0, v[250:251]
	global_load_dwordx4 v[200:203], v[194:195], off
	v_add_u32_e32 v250, 0x10, v199
	v_lshlrev_b32_e32 v250, 6, v250
	v_lshl_add_u64 v[194:195], v[160:161], 0, v[250:251]
	global_load_dwordx4 v[204:207], v[194:195], off
	v_add_u32_e32 v250, 0x20, v199
	v_lshlrev_b32_e32 v250, 6, v250
	v_lshl_add_u64 v[194:195], v[160:161], 0, v[250:251]
	global_load_dwordx4 v[150:153], v[194:195], off
	v_add_u32_e32 v250, 0x30, v199
	v_lshlrev_b32_e32 v250, 6, v250
	v_lshl_add_u64 v[194:195], v[160:161], 0, v[250:251]
	global_load_dwordx4 v[146:149], v[194:195], off
	v_add_u32_e32 v250, 0x80, v199
	v_lshlrev_b32_e32 v250, 6, v250
	v_lshl_add_u64 v[194:195], v[160:161], 0, v[250:251]
	global_load_dwordx4 v[142:145], v[194:195], off
	v_add_u32_e32 v250, 0x90, v199
	v_lshlrev_b32_e32 v250, 6, v250
	v_lshl_add_u64 v[194:195], v[160:161], 0, v[250:251]
	global_load_dwordx4 v[138:141], v[194:195], off
	v_add_u32_e32 v250, 0xa0, v199
	v_lshlrev_b32_e32 v250, 6, v250
	v_lshl_add_u64 v[194:195], v[160:161], 0, v[250:251]
	global_load_dwordx4 v[134:137], v[194:195], off
	v_add_u32_e32 v250, 0xb0, v199
	v_lshlrev_b32_e32 v250, 6, v250
	v_lshl_add_u64 v[194:195], v[160:161], 0, v[250:251]
	global_load_dwordx4 v[130:133], v[194:195], off
	v_or_b32_e32 v178, 16, v180
	v_or_b32_e32 v176, 32, v180
	v_or_b32_e32 v174, 48, v180
	v_add_u32_e32 v172, 0x80, v180
	v_add_u32_e32 v170, 0x90, v180
	v_add_u32_e32 v168, 0xa0, v180
	v_add_u32_e32 v166, 0xb0, v180
	s_and_b64 vcc, exec, s[58:59]
	s_cbranch_vccz .LBB0_947
	s_barrier
.LBB0_947:
	v_lshl_or_b32 v182, s5, 7, v190
	v_mov_b32_e32 v196, 0xbfb8aa3b
	v_mov_b32_e32 v194, 1.0
	v_lshlrev_b32_e32 v182, 1, v182
	v_pk_mul_f32 v[126:127], v[126:127], v[228:229] op_sel_hi:[1,0]
	v_pk_mul_f32 v[128:129], v[128:129], v[228:229] op_sel_hi:[1,0]
	v_pk_mul_f32 v[118:119], v[118:119], v[228:229] op_sel_hi:[1,0]
	v_pk_mul_f32 v[120:121], v[120:121], v[228:229] op_sel_hi:[1,0]
	v_pk_mul_f32 v[208:209], v[126:127], v[196:197] op_sel_hi:[1,0]
	v_pk_mul_f32 v[210:211], v[128:129], v[196:197] op_sel_hi:[1,0]
	v_pk_mul_f32 v[212:213], v[118:119], v[196:197] op_sel_hi:[1,0]
	v_pk_mul_f32 v[214:215], v[120:121], v[196:197] op_sel_hi:[1,0]
	v_pk_mul_f32 v[122:123], v[122:123], v[228:229] op_sel_hi:[1,0]
	v_pk_mul_f32 v[124:125], v[124:125], v[228:229] op_sel_hi:[1,0]
	v_pk_mul_f32 v[114:115], v[114:115], v[228:229] op_sel_hi:[1,0]
	v_pk_mul_f32 v[116:117], v[116:117], v[228:229] op_sel_hi:[1,0]
	v_exp_f32_e32 v208, v208
	v_exp_f32_e32 v209, v209
	v_exp_f32_e32 v210, v210
	v_exp_f32_e32 v211, v211
	v_exp_f32_e32 v212, v212
	v_exp_f32_e32 v213, v213
	v_exp_f32_e32 v214, v214
	v_exp_f32_e32 v215, v215
	v_pk_add_f32 v[208:209], v[208:209], v[194:195] op_sel_hi:[1,0]
	v_pk_add_f32 v[210:211], v[210:211], v[194:195] op_sel_hi:[1,0]
	v_pk_add_f32 v[212:213], v[212:213], v[194:195] op_sel_hi:[1,0]
	v_pk_add_f32 v[214:215], v[214:215], v[194:195] op_sel_hi:[1,0]
	v_rcp_f32_e32 v208, v208
	v_rcp_f32_e32 v209, v209
	v_rcp_f32_e32 v210, v210
	v_rcp_f32_e32 v211, v211
	v_rcp_f32_e32 v212, v212
	v_rcp_f32_e32 v213, v213
	v_rcp_f32_e32 v214, v214
	v_rcp_f32_e32 v215, v215
	v_pk_mul_f32 v[126:127], v[126:127], v[208:209]
	v_pk_mul_f32 v[128:129], v[128:129], v[210:211]
	v_pk_mul_f32 v[118:119], v[118:119], v[212:213]
	v_pk_mul_f32 v[120:121], v[120:121], v[214:215]
	v_pk_mul_f32 v[122:123], v[122:123], v[126:127]
	v_pk_mul_f32 v[124:125], v[124:125], v[128:129]
	v_pk_mul_f32 v[114:115], v[114:115], v[118:119]
	v_pk_mul_f32 v[116:117], v[116:117], v[120:121]
	v_cvt_pk_bf16_f32 v126, v122, v123
	v_cvt_pk_bf16_f32 v127, v124, v125
	v_cvt_pk_bf16_f32 v128, v114, v115
	v_cvt_pk_bf16_f32 v129, v116, v117
	v_mad_u32_u24 v118, v180, s31, v182
	global_store_dwordx4 v118, v[126:129], s[54:55]
	v_pk_mul_f32 v[110:111], v[110:111], v[230:231] op_sel_hi:[1,0]
	v_pk_mul_f32 v[112:113], v[112:113], v[230:231] op_sel_hi:[1,0]
	v_pk_mul_f32 v[102:103], v[102:103], v[230:231] op_sel_hi:[1,0]
	v_pk_mul_f32 v[104:105], v[104:105], v[230:231] op_sel_hi:[1,0]
	v_pk_mul_f32 v[216:217], v[110:111], v[196:197] op_sel_hi:[1,0]
	v_pk_mul_f32 v[218:219], v[112:113], v[196:197] op_sel_hi:[1,0]
	v_pk_mul_f32 v[220:221], v[102:103], v[196:197] op_sel_hi:[1,0]
	v_pk_mul_f32 v[222:223], v[104:105], v[196:197] op_sel_hi:[1,0]
	v_pk_mul_f32 v[106:107], v[106:107], v[230:231] op_sel_hi:[1,0]
	v_pk_mul_f32 v[108:109], v[108:109], v[230:231] op_sel_hi:[1,0]
	v_pk_mul_f32 v[98:99], v[98:99], v[230:231] op_sel_hi:[1,0]
	v_pk_mul_f32 v[100:101], v[100:101], v[230:231] op_sel_hi:[1,0]
	v_exp_f32_e32 v216, v216
	v_exp_f32_e32 v217, v217
	v_exp_f32_e32 v218, v218
	v_exp_f32_e32 v219, v219
	v_exp_f32_e32 v220, v220
	v_exp_f32_e32 v221, v221
	v_exp_f32_e32 v222, v222
	v_exp_f32_e32 v223, v223
	v_pk_add_f32 v[216:217], v[216:217], v[194:195] op_sel_hi:[1,0]
	v_pk_add_f32 v[218:219], v[218:219], v[194:195] op_sel_hi:[1,0]
	v_pk_add_f32 v[220:221], v[220:221], v[194:195] op_sel_hi:[1,0]
	v_pk_add_f32 v[222:223], v[222:223], v[194:195] op_sel_hi:[1,0]
	v_rcp_f32_e32 v216, v216
	v_rcp_f32_e32 v217, v217
	v_rcp_f32_e32 v218, v218
	v_rcp_f32_e32 v219, v219
	v_rcp_f32_e32 v220, v220
	v_rcp_f32_e32 v221, v221
	v_rcp_f32_e32 v222, v222
	v_rcp_f32_e32 v223, v223
	v_pk_mul_f32 v[110:111], v[110:111], v[216:217]
	v_pk_mul_f32 v[112:113], v[112:113], v[218:219]
	v_pk_mul_f32 v[102:103], v[102:103], v[220:221]
	v_pk_mul_f32 v[104:105], v[104:105], v[222:223]
	v_pk_mul_f32 v[106:107], v[106:107], v[110:111]
	v_pk_mul_f32 v[108:109], v[108:109], v[112:113]
	v_pk_mul_f32 v[98:99], v[98:99], v[102:103]
	v_pk_mul_f32 v[100:101], v[100:101], v[104:105]
	v_cvt_pk_bf16_f32 v110, v106, v107
	v_cvt_pk_bf16_f32 v111, v108, v109
	v_cvt_pk_bf16_f32 v112, v98, v99
	v_cvt_pk_bf16_f32 v113, v100, v101
	v_mad_u32_u24 v102, v178, s31, v182
	global_store_dwordx4 v102, v[110:113], s[54:55]
	v_pk_mul_f32 v[92:93], v[92:93], v[232:233] op_sel_hi:[1,0]
	v_pk_mul_f32 v[94:95], v[94:95], v[232:233] op_sel_hi:[1,0]
	v_pk_mul_f32 v[84:85], v[84:85], v[232:233] op_sel_hi:[1,0]
	v_pk_mul_f32 v[86:87], v[86:87], v[232:233] op_sel_hi:[1,0]
	v_pk_mul_f32 v[208:209], v[92:93], v[196:197] op_sel_hi:[1,0]
	v_pk_mul_f32 v[210:211], v[94:95], v[196:197] op_sel_hi:[1,0]
	v_pk_mul_f32 v[212:213], v[84:85], v[196:197] op_sel_hi:[1,0]
	v_pk_mul_f32 v[214:215], v[86:87], v[196:197] op_sel_hi:[1,0]
	v_pk_mul_f32 v[88:89], v[88:89], v[232:233] op_sel_hi:[1,0]
	v_pk_mul_f32 v[90:91], v[90:91], v[232:233] op_sel_hi:[1,0]
	v_pk_mul_f32 v[80:81], v[80:81], v[232:233] op_sel_hi:[1,0]
	v_pk_mul_f32 v[82:83], v[82:83], v[232:233] op_sel_hi:[1,0]
	v_exp_f32_e32 v208, v208
	v_exp_f32_e32 v209, v209
	v_exp_f32_e32 v210, v210
	v_exp_f32_e32 v211, v211
	v_exp_f32_e32 v212, v212
	v_exp_f32_e32 v213, v213
	v_exp_f32_e32 v214, v214
	v_exp_f32_e32 v215, v215
	v_pk_add_f32 v[208:209], v[208:209], v[194:195] op_sel_hi:[1,0]
	v_pk_add_f32 v[210:211], v[210:211], v[194:195] op_sel_hi:[1,0]
	v_pk_add_f32 v[212:213], v[212:213], v[194:195] op_sel_hi:[1,0]
	v_pk_add_f32 v[214:215], v[214:215], v[194:195] op_sel_hi:[1,0]
	v_rcp_f32_e32 v208, v208
	v_rcp_f32_e32 v209, v209
	v_rcp_f32_e32 v210, v210
	v_rcp_f32_e32 v211, v211
	v_rcp_f32_e32 v212, v212
	v_rcp_f32_e32 v213, v213
	v_rcp_f32_e32 v214, v214
	v_rcp_f32_e32 v215, v215
	v_pk_mul_f32 v[92:93], v[92:93], v[208:209]
	v_pk_mul_f32 v[94:95], v[94:95], v[210:211]
	v_pk_mul_f32 v[84:85], v[84:85], v[212:213]
	v_pk_mul_f32 v[86:87], v[86:87], v[214:215]
	v_pk_mul_f32 v[88:89], v[88:89], v[92:93]
	v_pk_mul_f32 v[90:91], v[90:91], v[94:95]
	v_pk_mul_f32 v[80:81], v[80:81], v[84:85]
	v_pk_mul_f32 v[82:83], v[82:83], v[86:87]
	v_cvt_pk_bf16_f32 v92, v88, v89
	v_cvt_pk_bf16_f32 v93, v90, v91
	v_cvt_pk_bf16_f32 v94, v80, v81
	v_cvt_pk_bf16_f32 v95, v82, v83
	v_mad_u32_u24 v84, v176, s31, v182
	global_store_dwordx4 v84, v[92:95], s[54:55]
	v_pk_mul_f32 v[76:77], v[76:77], v[234:235] op_sel_hi:[1,0]
	v_pk_mul_f32 v[78:79], v[78:79], v[234:235] op_sel_hi:[1,0]
	v_pk_mul_f32 v[68:69], v[68:69], v[234:235] op_sel_hi:[1,0]
	v_pk_mul_f32 v[70:71], v[70:71], v[234:235] op_sel_hi:[1,0]
	v_pk_mul_f32 v[216:217], v[76:77], v[196:197] op_sel_hi:[1,0]
	v_pk_mul_f32 v[218:219], v[78:79], v[196:197] op_sel_hi:[1,0]
	v_pk_mul_f32 v[220:221], v[68:69], v[196:197] op_sel_hi:[1,0]
	v_pk_mul_f32 v[222:223], v[70:71], v[196:197] op_sel_hi:[1,0]
	v_pk_mul_f32 v[72:73], v[72:73], v[234:235] op_sel_hi:[1,0]
	v_pk_mul_f32 v[74:75], v[74:75], v[234:235] op_sel_hi:[1,0]
	v_pk_mul_f32 v[64:65], v[64:65], v[234:235] op_sel_hi:[1,0]
	v_pk_mul_f32 v[66:67], v[66:67], v[234:235] op_sel_hi:[1,0]
	v_exp_f32_e32 v216, v216
	v_exp_f32_e32 v217, v217
	v_exp_f32_e32 v218, v218
	v_exp_f32_e32 v219, v219
	v_exp_f32_e32 v220, v220
	v_exp_f32_e32 v221, v221
	v_exp_f32_e32 v222, v222
	v_exp_f32_e32 v223, v223
	v_pk_add_f32 v[216:217], v[216:217], v[194:195] op_sel_hi:[1,0]
	v_pk_add_f32 v[218:219], v[218:219], v[194:195] op_sel_hi:[1,0]
	v_pk_add_f32 v[220:221], v[220:221], v[194:195] op_sel_hi:[1,0]
	v_pk_add_f32 v[222:223], v[222:223], v[194:195] op_sel_hi:[1,0]
	v_rcp_f32_e32 v216, v216
	v_rcp_f32_e32 v217, v217
	v_rcp_f32_e32 v218, v218
	v_rcp_f32_e32 v219, v219
	v_rcp_f32_e32 v220, v220
	v_rcp_f32_e32 v221, v221
	v_rcp_f32_e32 v222, v222
	v_rcp_f32_e32 v223, v223
	v_pk_mul_f32 v[76:77], v[76:77], v[216:217]
	v_pk_mul_f32 v[78:79], v[78:79], v[218:219]
	v_pk_mul_f32 v[68:69], v[68:69], v[220:221]
	v_pk_mul_f32 v[70:71], v[70:71], v[222:223]
	v_pk_mul_f32 v[72:73], v[72:73], v[76:77]
	v_pk_mul_f32 v[74:75], v[74:75], v[78:79]
	v_pk_mul_f32 v[64:65], v[64:65], v[68:69]
	v_pk_mul_f32 v[66:67], v[66:67], v[70:71]
	v_cvt_pk_bf16_f32 v76, v72, v73
	v_cvt_pk_bf16_f32 v77, v74, v75
	v_cvt_pk_bf16_f32 v78, v64, v65
	v_cvt_pk_bf16_f32 v79, v66, v67
	v_mad_u32_u24 v68, v174, s31, v182
	global_store_dwordx4 v68, v[76:79], s[54:55]
	v_pk_mul_f32 v[60:61], v[60:61], v[236:237] op_sel_hi:[1,0]
	v_pk_mul_f32 v[62:63], v[62:63], v[236:237] op_sel_hi:[1,0]
	v_pk_mul_f32 v[52:53], v[52:53], v[236:237] op_sel_hi:[1,0]
	v_pk_mul_f32 v[54:55], v[54:55], v[236:237] op_sel_hi:[1,0]
	v_pk_mul_f32 v[208:209], v[60:61], v[196:197] op_sel_hi:[1,0]
	v_pk_mul_f32 v[210:211], v[62:63], v[196:197] op_sel_hi:[1,0]
	v_pk_mul_f32 v[212:213], v[52:53], v[196:197] op_sel_hi:[1,0]
	v_pk_mul_f32 v[214:215], v[54:55], v[196:197] op_sel_hi:[1,0]
	v_pk_mul_f32 v[56:57], v[56:57], v[236:237] op_sel_hi:[1,0]
	v_pk_mul_f32 v[58:59], v[58:59], v[236:237] op_sel_hi:[1,0]
	v_pk_mul_f32 v[48:49], v[48:49], v[236:237] op_sel_hi:[1,0]
	v_pk_mul_f32 v[50:51], v[50:51], v[236:237] op_sel_hi:[1,0]
	v_exp_f32_e32 v208, v208
	v_exp_f32_e32 v209, v209
	v_exp_f32_e32 v210, v210
	v_exp_f32_e32 v211, v211
	v_exp_f32_e32 v212, v212
	v_exp_f32_e32 v213, v213
	v_exp_f32_e32 v214, v214
	v_exp_f32_e32 v215, v215
	v_pk_add_f32 v[208:209], v[208:209], v[194:195] op_sel_hi:[1,0]
	v_pk_add_f32 v[210:211], v[210:211], v[194:195] op_sel_hi:[1,0]
	v_pk_add_f32 v[212:213], v[212:213], v[194:195] op_sel_hi:[1,0]
	v_pk_add_f32 v[214:215], v[214:215], v[194:195] op_sel_hi:[1,0]
	v_rcp_f32_e32 v208, v208
	v_rcp_f32_e32 v209, v209
	v_rcp_f32_e32 v210, v210
	v_rcp_f32_e32 v211, v211
	v_rcp_f32_e32 v212, v212
	v_rcp_f32_e32 v213, v213
	v_rcp_f32_e32 v214, v214
	v_rcp_f32_e32 v215, v215
	v_pk_mul_f32 v[60:61], v[60:61], v[208:209]
	v_pk_mul_f32 v[62:63], v[62:63], v[210:211]
	v_pk_mul_f32 v[52:53], v[52:53], v[212:213]
	v_pk_mul_f32 v[54:55], v[54:55], v[214:215]
	v_pk_mul_f32 v[56:57], v[56:57], v[60:61]
	v_pk_mul_f32 v[58:59], v[58:59], v[62:63]
	v_pk_mul_f32 v[48:49], v[48:49], v[52:53]
	v_pk_mul_f32 v[50:51], v[50:51], v[54:55]
	v_cvt_pk_bf16_f32 v60, v56, v57
	v_cvt_pk_bf16_f32 v61, v58, v59
	v_cvt_pk_bf16_f32 v62, v48, v49
	v_cvt_pk_bf16_f32 v63, v50, v51
	v_mad_u32_u24 v52, v172, s31, v182
	global_store_dwordx4 v52, v[60:63], s[54:55]
	v_pk_mul_f32 v[44:45], v[44:45], v[238:239] op_sel_hi:[1,0]
	v_pk_mul_f32 v[46:47], v[46:47], v[238:239] op_sel_hi:[1,0]
	v_pk_mul_f32 v[36:37], v[36:37], v[238:239] op_sel_hi:[1,0]
	v_pk_mul_f32 v[38:39], v[38:39], v[238:239] op_sel_hi:[1,0]
	v_pk_mul_f32 v[216:217], v[44:45], v[196:197] op_sel_hi:[1,0]
	v_pk_mul_f32 v[218:219], v[46:47], v[196:197] op_sel_hi:[1,0]
	v_pk_mul_f32 v[220:221], v[36:37], v[196:197] op_sel_hi:[1,0]
	v_pk_mul_f32 v[222:223], v[38:39], v[196:197] op_sel_hi:[1,0]
	v_pk_mul_f32 v[40:41], v[40:41], v[238:239] op_sel_hi:[1,0]
	v_pk_mul_f32 v[42:43], v[42:43], v[238:239] op_sel_hi:[1,0]
	v_pk_mul_f32 v[32:33], v[32:33], v[238:239] op_sel_hi:[1,0]
	v_pk_mul_f32 v[34:35], v[34:35], v[238:239] op_sel_hi:[1,0]
	v_exp_f32_e32 v216, v216
	v_exp_f32_e32 v217, v217
	v_exp_f32_e32 v218, v218
	v_exp_f32_e32 v219, v219
	v_exp_f32_e32 v220, v220
	v_exp_f32_e32 v221, v221
	v_exp_f32_e32 v222, v222
	v_exp_f32_e32 v223, v223
	v_pk_add_f32 v[216:217], v[216:217], v[194:195] op_sel_hi:[1,0]
	v_pk_add_f32 v[218:219], v[218:219], v[194:195] op_sel_hi:[1,0]
	v_pk_add_f32 v[220:221], v[220:221], v[194:195] op_sel_hi:[1,0]
	v_pk_add_f32 v[222:223], v[222:223], v[194:195] op_sel_hi:[1,0]
	v_rcp_f32_e32 v216, v216
	v_rcp_f32_e32 v217, v217
	v_rcp_f32_e32 v218, v218
	v_rcp_f32_e32 v219, v219
	v_rcp_f32_e32 v220, v220
	v_rcp_f32_e32 v221, v221
	v_rcp_f32_e32 v222, v222
	v_rcp_f32_e32 v223, v223
	v_pk_mul_f32 v[44:45], v[44:45], v[216:217]
	v_pk_mul_f32 v[46:47], v[46:47], v[218:219]
	v_pk_mul_f32 v[36:37], v[36:37], v[220:221]
	v_pk_mul_f32 v[38:39], v[38:39], v[222:223]
	v_pk_mul_f32 v[40:41], v[40:41], v[44:45]
	v_pk_mul_f32 v[42:43], v[42:43], v[46:47]
	v_pk_mul_f32 v[32:33], v[32:33], v[36:37]
	v_pk_mul_f32 v[34:35], v[34:35], v[38:39]
	v_cvt_pk_bf16_f32 v44, v40, v41
	v_cvt_pk_bf16_f32 v45, v42, v43
	v_cvt_pk_bf16_f32 v46, v32, v33
	v_cvt_pk_bf16_f32 v47, v34, v35
	v_mad_u32_u24 v36, v170, s31, v182
	global_store_dwordx4 v36, v[44:47], s[54:55]
	v_pk_mul_f32 v[28:29], v[28:29], v[242:243] op_sel_hi:[1,0]
	v_pk_mul_f32 v[30:31], v[30:31], v[242:243] op_sel_hi:[1,0]
	v_pk_mul_f32 v[20:21], v[20:21], v[242:243] op_sel_hi:[1,0]
	v_pk_mul_f32 v[22:23], v[22:23], v[242:243] op_sel_hi:[1,0]
	v_pk_mul_f32 v[208:209], v[28:29], v[196:197] op_sel_hi:[1,0]
	v_pk_mul_f32 v[210:211], v[30:31], v[196:197] op_sel_hi:[1,0]
	v_pk_mul_f32 v[212:213], v[20:21], v[196:197] op_sel_hi:[1,0]
	v_pk_mul_f32 v[214:215], v[22:23], v[196:197] op_sel_hi:[1,0]
	v_pk_mul_f32 v[24:25], v[24:25], v[242:243] op_sel_hi:[1,0]
	v_pk_mul_f32 v[26:27], v[26:27], v[242:243] op_sel_hi:[1,0]
	v_pk_mul_f32 v[16:17], v[16:17], v[242:243] op_sel_hi:[1,0]
	v_pk_mul_f32 v[18:19], v[18:19], v[242:243] op_sel_hi:[1,0]
	v_exp_f32_e32 v208, v208
	v_exp_f32_e32 v209, v209
	v_exp_f32_e32 v210, v210
	v_exp_f32_e32 v211, v211
	v_exp_f32_e32 v212, v212
	v_exp_f32_e32 v213, v213
	v_exp_f32_e32 v214, v214
	v_exp_f32_e32 v215, v215
	v_pk_add_f32 v[208:209], v[208:209], v[194:195] op_sel_hi:[1,0]
	v_pk_add_f32 v[210:211], v[210:211], v[194:195] op_sel_hi:[1,0]
	v_pk_add_f32 v[212:213], v[212:213], v[194:195] op_sel_hi:[1,0]
	v_pk_add_f32 v[214:215], v[214:215], v[194:195] op_sel_hi:[1,0]
	v_rcp_f32_e32 v208, v208
	v_rcp_f32_e32 v209, v209
	v_rcp_f32_e32 v210, v210
	v_rcp_f32_e32 v211, v211
	v_rcp_f32_e32 v212, v212
	v_rcp_f32_e32 v213, v213
	v_rcp_f32_e32 v214, v214
	v_rcp_f32_e32 v215, v215
	v_pk_mul_f32 v[28:29], v[28:29], v[208:209]
	v_pk_mul_f32 v[30:31], v[30:31], v[210:211]
	v_pk_mul_f32 v[20:21], v[20:21], v[212:213]
	v_pk_mul_f32 v[22:23], v[22:23], v[214:215]
	v_pk_mul_f32 v[24:25], v[24:25], v[28:29]
	v_pk_mul_f32 v[26:27], v[26:27], v[30:31]
	v_pk_mul_f32 v[16:17], v[16:17], v[20:21]
	v_pk_mul_f32 v[18:19], v[18:19], v[22:23]
	v_cvt_pk_bf16_f32 v28, v24, v25
	v_cvt_pk_bf16_f32 v29, v26, v27
	v_cvt_pk_bf16_f32 v30, v16, v17
	v_cvt_pk_bf16_f32 v31, v18, v19
	v_mad_u32_u24 v20, v168, s31, v182
	global_store_dwordx4 v20, v[28:31], s[54:55]
	v_pk_mul_f32 v[12:13], v[12:13], v[244:245] op_sel_hi:[1,0]
	v_pk_mul_f32 v[14:15], v[14:15], v[244:245] op_sel_hi:[1,0]
	v_pk_mul_f32 v[4:5], v[4:5], v[244:245] op_sel_hi:[1,0]
	v_pk_mul_f32 v[6:7], v[6:7], v[244:245] op_sel_hi:[1,0]
	v_pk_mul_f32 v[216:217], v[12:13], v[196:197] op_sel_hi:[1,0]
	v_pk_mul_f32 v[218:219], v[14:15], v[196:197] op_sel_hi:[1,0]
	v_pk_mul_f32 v[220:221], v[4:5], v[196:197] op_sel_hi:[1,0]
	v_pk_mul_f32 v[222:223], v[6:7], v[196:197] op_sel_hi:[1,0]
	v_pk_mul_f32 v[8:9], v[8:9], v[244:245] op_sel_hi:[1,0]
	v_pk_mul_f32 v[10:11], v[10:11], v[244:245] op_sel_hi:[1,0]
	v_pk_mul_f32 v[0:1], v[0:1], v[244:245] op_sel_hi:[1,0]
	v_pk_mul_f32 v[2:3], v[2:3], v[244:245] op_sel_hi:[1,0]
	v_exp_f32_e32 v216, v216
	v_exp_f32_e32 v217, v217
	v_exp_f32_e32 v218, v218
	v_exp_f32_e32 v219, v219
	v_exp_f32_e32 v220, v220
	v_exp_f32_e32 v221, v221
	v_exp_f32_e32 v222, v222
	v_exp_f32_e32 v223, v223
	v_pk_add_f32 v[216:217], v[216:217], v[194:195] op_sel_hi:[1,0]
	v_pk_add_f32 v[218:219], v[218:219], v[194:195] op_sel_hi:[1,0]
	v_pk_add_f32 v[220:221], v[220:221], v[194:195] op_sel_hi:[1,0]
	v_pk_add_f32 v[222:223], v[222:223], v[194:195] op_sel_hi:[1,0]
	v_rcp_f32_e32 v216, v216
	v_rcp_f32_e32 v217, v217
	v_rcp_f32_e32 v218, v218
	v_rcp_f32_e32 v219, v219
	v_rcp_f32_e32 v220, v220
	v_rcp_f32_e32 v221, v221
	v_rcp_f32_e32 v222, v222
	v_rcp_f32_e32 v223, v223
	v_pk_mul_f32 v[12:13], v[12:13], v[216:217]
	v_pk_mul_f32 v[14:15], v[14:15], v[218:219]
	v_pk_mul_f32 v[4:5], v[4:5], v[220:221]
	v_pk_mul_f32 v[6:7], v[6:7], v[222:223]
	v_pk_mul_f32 v[8:9], v[8:9], v[12:13]
	v_pk_mul_f32 v[10:11], v[10:11], v[14:15]
	v_pk_mul_f32 v[0:1], v[0:1], v[4:5]
	v_pk_mul_f32 v[2:3], v[2:3], v[6:7]
	v_cvt_pk_bf16_f32 v12, v8, v9
	v_cvt_pk_bf16_f32 v13, v10, v11
	v_cvt_pk_bf16_f32 v14, v0, v1
	v_cvt_pk_bf16_f32 v15, v2, v3
	v_mad_u32_u24 v4, v166, s31, v182
	global_store_dwordx4 v4, v[12:15], s[54:55]
	s_waitcnt vmcnt(8)
	v_xor_b32_e32 v250, 16, v248
	v_xor_b32_e32 v251, 32, v248
	v_lshlrev_b32_e32 v250, 2, v250
	v_lshlrev_b32_e32 v251, 2, v251
	v_mov_b32_e32 v199, 0x358637bd
	v_add_f32_e32 v200, v201, v200
	v_add_f32_e32 v202, v202, v203
	v_add_f32_e32 v204, v205, v204
	v_add_f32_e32 v206, v206, v207
	v_add_f32_e32 v150, v151, v150
	v_add_f32_e32 v152, v152, v153
	v_add_f32_e32 v146, v147, v146
	v_add_f32_e32 v148, v148, v149
	v_add_f32_e32 v142, v143, v142
	v_add_f32_e32 v144, v144, v145
	v_add_f32_e32 v138, v139, v138
	v_add_f32_e32 v140, v140, v141
	v_add_f32_e32 v134, v135, v134
	v_add_f32_e32 v136, v136, v137
	v_add_f32_e32 v130, v131, v130
	v_add_f32_e32 v132, v132, v133
	v_add_f32_e32 v200, v200, v202
	v_add_f32_e32 v204, v204, v206
	v_add_f32_e32 v150, v150, v152
	v_add_f32_e32 v146, v146, v148
	v_add_f32_e32 v142, v142, v144
	v_add_f32_e32 v138, v138, v140
	v_add_f32_e32 v134, v134, v136
	v_add_f32_e32 v130, v130, v132
	ds_bpermute_b32 v201, v250, v200
	ds_bpermute_b32 v205, v250, v204
	ds_bpermute_b32 v151, v250, v150
	ds_bpermute_b32 v147, v250, v146
	ds_bpermute_b32 v143, v250, v142
	ds_bpermute_b32 v139, v250, v138
	ds_bpermute_b32 v135, v250, v134
	ds_bpermute_b32 v131, v250, v130
	s_waitcnt lgkmcnt(0)
	v_add_f32_e32 v200, v200, v201
	v_add_f32_e32 v204, v204, v205
	v_add_f32_e32 v150, v150, v151
	v_add_f32_e32 v146, v146, v147
	v_add_f32_e32 v142, v142, v143
	v_add_f32_e32 v138, v138, v139
	v_add_f32_e32 v134, v134, v135
	v_add_f32_e32 v130, v130, v131
	ds_bpermute_b32 v201, v251, v200
	ds_bpermute_b32 v205, v251, v204
	ds_bpermute_b32 v151, v251, v150
	ds_bpermute_b32 v147, v251, v146
	ds_bpermute_b32 v143, v251, v142
	ds_bpermute_b32 v139, v251, v138
	ds_bpermute_b32 v135, v251, v134
	ds_bpermute_b32 v131, v251, v130
	s_waitcnt lgkmcnt(0)
	v_add_f32_e32 v200, v200, v201
	v_add_f32_e32 v204, v204, v205
	v_add_f32_e32 v150, v150, v151
	v_add_f32_e32 v146, v146, v147
	v_add_f32_e32 v142, v142, v143
	v_add_f32_e32 v138, v138, v139
	v_add_f32_e32 v134, v134, v135
	v_add_f32_e32 v130, v130, v131
	v_fma_f32 v200, v200, s28, v199
	v_fma_f32 v204, v204, s28, v199
	v_fma_f32 v150, v150, s28, v199
	v_fma_f32 v146, v146, s28, v199
	v_fma_f32 v142, v142, s28, v199
	v_fma_f32 v138, v138, s28, v199
	v_fma_f32 v134, v134, s28, v199
	v_fma_f32 v130, v130, s28, v199
	v_rsq_f32_e32 v228, v200
	v_rsq_f32_e32 v230, v204
	v_rsq_f32_e32 v232, v150
	v_rsq_f32_e32 v234, v146
	v_rsq_f32_e32 v236, v142
	v_rsq_f32_e32 v238, v138
	v_rsq_f32_e32 v242, v134
	v_rsq_f32_e32 v244, v130
	s_andn2_b64 vcc, exec, s[0:1]
	s_mov_b64 s[4:5], -1
	s_cbranch_vccnz .LBB0_940
	s_andn2_b64 vcc, exec, s[6:7]
	s_cbranch_vccnz .LBB0_939
	s_barrier
	s_branch .LBB0_939
